# sample rows: split-K reduction + next norm done at the end of the residual GEMM phase; 8 norm phases and barriers removed
# speedup vs baseline: 1.1316x; 1.0334x over previous
.LBB0_15:
	v_readlane_b32 s0, v252, 3
	s_cmp_eq_u32 s0, 38
	s_cbranch_scc1 .Lph_skip
	s_cmp_lt_u32 s0, 3
	s_cbranch_scc1 .Lph_noskip
	s_add_i32 s2, s0, -2
	s_mul_hi_u32 s3, s2, 0x38e38e39
	s_lshr_b32 s3, s3, 1
	s_mul_i32 s3, s3, 9
	s_sub_i32 s2, s2, s3
	s_cmp_eq_u32 s2, 0
	s_cbranch_scc1 .Lph_skip
	s_cmp_lg_u32 s2, 5
	s_cbranch_scc1 .Lph_noskip
.Lph_skip:
	s_add_i32 s4, s0, 1
	s_branch .LBB0_13

.LBB0_307:
	v_add_u32_e32 v214, 0xffffc000, v192
	s_ashr_i32 s31, s38, 13
	v_lshrrev_b32_e32 v134, 3, v214
	v_lshlrev_b64 v[196:197], 2, v[194:195]
	v_cmp_gt_i32_e32 vcc, s85, v192
	v_or_b32_e32 v134, 2, v134
	v_mov_b32_e32 v136, s31
	v_lshl_add_u64 v[198:199], s[18:19], 0, v[196:197]
	v_cndmask_b32_e32 v134, v134, v136, vcc
	v_mad_i64_i32 v[134:135], s[34:35], v134, s88, v[198:199]
	v_add_u32_e32 v204, 0xffffc010, v192
	global_load_dwordx4 v[210:213], v[134:135], off
	global_load_dwordx4 v[220:223], v[134:135], off offset:64
	global_load_dwordx4 v[224:227], v[134:135], off offset:512
	global_load_dwordx4 v[244:247], v[134:135], off offset:576
	v_lshrrev_b32_e32 v134, 3, v204
	v_cmp_gt_i32_e32 vcc, s85, v190
	v_add_u32_e32 v134, 2, v134
	v_add_u32_e32 v202, 0xffffc020, v192
	v_cndmask_b32_e32 v134, v134, v136, vcc
	v_mad_i64_i32 v[134:135], s[34:35], v134, s88, v[198:199]
	global_load_dwordx4 v[178:181], v[134:135], off
	global_load_dwordx4 v[174:177], v[134:135], off offset:64
	global_load_dwordx4 v[170:173], v[134:135], off offset:512
	global_load_dwordx4 v[162:165], v[134:135], off offset:576
	v_lshrrev_b32_e32 v134, 3, v202
	v_cmp_gt_i32_e32 vcc, s85, v188
	v_or_b32_e32 v134, 2, v134
	v_add_u32_e32 v200, 0xffffc030, v192
	v_cndmask_b32_e32 v134, v134, v136, vcc
	v_mad_i64_i32 v[134:135], s[34:35], v134, s88, v[198:199]
	global_load_dwordx4 v[166:169], v[134:135], off
	global_load_dwordx4 v[158:161], v[134:135], off offset:64
	global_load_dwordx4 v[154:157], v[134:135], off offset:512
	global_load_dwordx4 v[146:149], v[134:135], off offset:576
	v_lshrrev_b32_e32 v134, 3, v200
	v_cmp_gt_i32_e32 vcc, s85, v186
	v_add_u32_e32 v134, 2, v134
	s_ashr_i32 s31, s30, 31
	v_cndmask_b32_e32 v134, v134, v136, vcc
	v_mad_i64_i32 v[134:135], s[34:35], v134, s88, v[198:199]
	global_load_dwordx4 v[150:153], v[134:135], off
	global_load_dwordx4 v[142:145], v[134:135], off offset:64
	global_load_dwordx4 v[138:141], v[134:135], off offset:512
	s_nop 0
	global_load_dwordx4 v[134:137], v[134:135], off offset:576
	s_abs_i32 s30, s30
	s_mul_hi_u32 s34, s30, s72
	s_mul_i32 s35, s34, s42
	s_sub_i32 s30, s30, s35
	s_add_i32 s35, s34, 1
	s_sub_i32 s36, s30, s42
	s_cmp_ge_u32 s30, s42
	s_cselect_b32 s34, s35, s34
	s_cselect_b32 s30, s36, s30
	s_add_i32 s35, s34, 1
	s_cmp_ge_u32 s30, s42
	s_cselect_b32 s30, s35, s34
	s_xor_b32 s30, s30, s31
	s_sub_i32 s30, s30, s31
	s_ashr_i32 s31, s30, 31
	s_lshl_b64 s[30:31], s[30:31], 22
	s_add_u32 s30, s60, s30
	v_ashrrev_i32_e32 v205, 31, v204
	s_addc_u32 s31, s61, s31
	v_lshlrev_b64 v[204:205], 12, v[204:205]
	v_ashrrev_i32_e32 v215, 31, v214
	v_lshl_add_u64 v[204:205], s[30:31], 0, v[204:205]
	v_lshlrev_b64 v[214:215], 12, v[214:215]
	v_lshl_add_u64 v[204:205], v[204:205], 0, v[196:197]
	v_ashrrev_i32_e32 v203, 31, v202
	v_lshl_add_u64 v[214:215], s[30:31], 0, v[214:215]
	v_lshl_add_u64 v[214:215], v[214:215], 0, v[196:197]
	v_ashrrev_i32_e32 v201, 31, v200
	s_addk_i32 s38, 0x80
	s_ashr_i32 s34, s38, 13
	s_movk_i32 s35, 0x3f80
	v_cmp_gt_i32_e32 vcc, s35, v192
	v_mov_b32_e32 v187, s34
	v_add_u32_e32 v216, 0xffffc090, v192
	v_ashrrev_i32_e32 v217, 31, v216
	s_waitcnt vmcnt(0)
	v_pk_mul_f32 v[212:213], v[132:133], v[212:213]
	v_pk_mul_f32 v[210:211], v[130:131], v[210:211]
	global_store_dwordx4 v[214:215], v[210:213], off sc1
	v_pk_mul_f32 v[180:181], v[116:117], v[180:181]
	s_nop 0
	v_pk_mul_f32 v[212:213], v[128:129], v[222:223]
	v_pk_mul_f32 v[172:173], v[108:109], v[172:173]
	v_pk_mul_f32 v[164:165], v[104:105], v[164:165]
	v_pk_mul_f32 v[162:163], v[102:103], v[162:163]
	global_store_dwordx4 v[204:205], v[162:165], off offset:576 sc1
	v_pk_mul_f32 v[170:171], v[106:107], v[170:171]
	v_pk_mul_f32 v[210:211], v[126:127], v[220:221]
	v_lshlrev_b64 v[162:163], 12, v[202:203]
	v_lshl_add_u64 v[162:163], s[30:31], 0, v[162:163]
	global_store_dwordx4 v[204:205], v[170:173], off offset:512 sc1
	v_pk_mul_f32 v[148:149], v[88:89], v[148:149]
	v_pk_mul_f32 v[146:147], v[86:87], v[146:147]
	v_lshl_add_u64 v[170:171], v[162:163], 0, v[196:197]
	global_store_dwordx4 v[214:215], v[210:213], off offset:64 sc1
	global_store_dwordx4 v[170:171], v[146:149], off offset:576 sc1
	v_pk_mul_f32 v[156:157], v[92:93], v[156:157]
	v_pk_mul_f32 v[212:213], v[124:125], v[226:227]
	v_pk_mul_f32 v[210:211], v[122:123], v[224:225]
	v_lshlrev_b64 v[146:147], 12, v[200:201]
	global_store_dwordx4 v[214:215], v[210:213], off offset:512 sc1
	v_pk_mul_f32 v[154:155], v[90:91], v[154:155]
	v_lshl_add_u64 v[146:147], s[30:31], 0, v[146:147]
	v_pk_mul_f32 v[212:213], v[120:121], v[246:247]
	v_pk_mul_f32 v[210:211], v[118:119], v[244:245]
	global_store_dwordx4 v[214:215], v[210:213], off offset:576 sc1
	global_store_dwordx4 v[170:171], v[154:157], off offset:512 sc1
	v_pk_mul_f32 v[136:137], v[72:73], v[136:137]
	v_pk_mul_f32 v[134:135], v[70:71], v[134:135]
	v_lshl_add_u64 v[154:155], v[146:147], 0, v[196:197]
	v_add_u32_e32 v214, 0xffffc080, v192
	global_store_dwordx4 v[154:155], v[134:137], off offset:576 sc1
	v_pk_mul_f32 v[178:179], v[114:115], v[178:179]
	v_pk_mul_f32 v[176:177], v[112:113], v[176:177]
	v_lshrrev_b32_e32 v134, 3, v214
	v_pk_mul_f32 v[174:175], v[110:111], v[174:175]
	v_pk_mul_f32 v[164:165], v[100:101], v[168:169]
	v_pk_mul_f32 v[162:163], v[98:99], v[166:167]
	v_pk_mul_f32 v[160:161], v[96:97], v[160:161]
	v_pk_mul_f32 v[158:159], v[94:95], v[158:159]
	v_pk_mul_f32 v[148:149], v[84:85], v[152:153]
	v_pk_mul_f32 v[146:147], v[82:83], v[150:151]
	v_pk_mul_f32 v[144:145], v[80:81], v[144:145]
	v_pk_mul_f32 v[142:143], v[78:79], v[142:143]
	v_pk_mul_f32 v[140:141], v[76:77], v[140:141]
	v_pk_mul_f32 v[138:139], v[74:75], v[138:139]
	v_or_b32_e32 v134, 2, v134
	global_store_dwordx4 v[204:205], v[178:181], off sc1
	global_store_dwordx4 v[204:205], v[174:177], off offset:64 sc1
	global_store_dwordx4 v[170:171], v[162:165], off sc1
	global_store_dwordx4 v[170:171], v[158:161], off offset:64 sc1
	global_store_dwordx4 v[154:155], v[146:149], off sc1
	global_store_dwordx4 v[154:155], v[142:145], off offset:64 sc1
	global_store_dwordx4 v[154:155], v[138:141], off offset:512 sc1
	v_cndmask_b32_e32 v134, v134, v187, vcc
	v_mad_i64_i32 v[146:147], s[34:35], v134, s88, v[198:199]
	global_load_dwordx4 v[134:137], v[146:147], off
	global_load_dwordx4 v[138:141], v[146:147], off offset:64
	global_load_dwordx4 v[142:145], v[146:147], off offset:512
	s_nop 0
	global_load_dwordx4 v[146:149], v[146:147], off offset:576
	s_movk_i32 s34, 0x3f70
	v_lshrrev_b32_e32 v150, 3, v216
	v_cmp_gt_i32_e32 vcc, s34, v192
	v_add_u32_e32 v150, 2, v150
	v_add_u32_e32 v224, 0xffffc0a0, v192
	v_cndmask_b32_e32 v150, v150, v187, vcc
	v_mad_i64_i32 v[162:163], s[34:35], v150, s88, v[198:199]
	global_load_dwordx4 v[150:153], v[162:163], off
	global_load_dwordx4 v[154:157], v[162:163], off offset:64
	global_load_dwordx4 v[158:161], v[162:163], off offset:512
	s_nop 0
	global_load_dwordx4 v[162:165], v[162:163], off offset:576
	s_movk_i32 s34, 0x3f60
	v_lshrrev_b32_e32 v166, 3, v224
	v_cmp_gt_i32_e32 vcc, s34, v192
	v_or_b32_e32 v166, 2, v166
	v_add_u32_e32 v226, 0xffffc0b0, v192
	v_cndmask_b32_e32 v166, v166, v187, vcc
	v_mad_i64_i32 v[178:179], s[34:35], v166, s88, v[198:199]
	global_load_dwordx4 v[166:169], v[178:179], off
	global_load_dwordx4 v[170:173], v[178:179], off offset:64
	global_load_dwordx4 v[174:177], v[178:179], off offset:512
	s_nop 0
	global_load_dwordx4 v[178:181], v[178:179], off offset:576
	v_lshrrev_b32_e32 v189, 3, v226
	v_cmp_gt_i32_e32 vcc, s94, v192
	v_add_u32_e32 v189, 2, v189
	v_ashrrev_i32_e32 v215, 31, v214
	v_cndmask_b32_e32 v187, v189, v187, vcc
	v_mad_i64_i32 v[220:221], s[34:35], v187, s88, v[198:199]
	global_load_dwordx4 v[198:201], v[220:221], off
	global_load_dwordx4 v[202:205], v[220:221], off offset:64
	global_load_dwordx4 v[210:213], v[220:221], off offset:512
	s_nop 0
	global_load_dwordx4 v[220:223], v[220:221], off offset:576
	v_lshlrev_b64 v[214:215], 12, v[214:215]
	v_lshl_add_u64 v[214:215], s[30:31], 0, v[214:215]
	v_lshl_add_u64 v[214:215], v[214:215], 0, v[196:197]
	v_ashrrev_i32_e32 v225, 31, v224
	v_ashrrev_i32_e32 v227, 31, v226
	s_waitcnt vmcnt(0)
	v_pk_mul_f32 v[136:137], v[68:69], v[136:137]
	v_pk_mul_f32 v[134:135], v[66:67], v[134:135]
	global_store_dwordx4 v[214:215], v[134:137], off sc1
	s_nop 1
	v_pk_mul_f32 v[136:137], v[64:65], v[140:141]
	v_pk_mul_f32 v[134:135], v[62:63], v[138:139]
	global_store_dwordx4 v[214:215], v[134:137], off offset:64 sc1
	s_nop 1
	v_pk_mul_f32 v[136:137], v[60:61], v[144:145]
	v_pk_mul_f32 v[134:135], v[58:59], v[142:143]
	global_store_dwordx4 v[214:215], v[134:137], off offset:512 sc1
	s_nop 1
	v_pk_mul_f32 v[136:137], v[56:57], v[148:149]
	v_pk_mul_f32 v[134:135], v[54:55], v[146:147]
	global_store_dwordx4 v[214:215], v[134:137], off offset:576 sc1
	s_nop 1
	v_lshlrev_b64 v[134:135], 12, v[216:217]
	v_lshl_add_u64 v[134:135], s[30:31], 0, v[134:135]
	v_lshl_add_u64 v[138:139], v[134:135], 0, v[196:197]
	v_pk_mul_f32 v[136:137], v[52:53], v[152:153]
	v_pk_mul_f32 v[134:135], v[50:51], v[150:151]
	global_store_dwordx4 v[138:139], v[134:137], off sc1
	s_nop 1
	v_pk_mul_f32 v[136:137], v[48:49], v[156:157]
	v_pk_mul_f32 v[134:135], v[46:47], v[154:155]
	global_store_dwordx4 v[138:139], v[134:137], off offset:64 sc1
	s_nop 1
	v_pk_mul_f32 v[136:137], v[44:45], v[160:161]
	v_pk_mul_f32 v[134:135], v[42:43], v[158:159]
	global_store_dwordx4 v[138:139], v[134:137], off offset:512 sc1
	s_nop 1
	v_pk_mul_f32 v[136:137], v[40:41], v[164:165]
	v_pk_mul_f32 v[134:135], v[38:39], v[162:163]
	global_store_dwordx4 v[138:139], v[134:137], off offset:576 sc1
	s_nop 1
	v_lshlrev_b64 v[134:135], 12, v[224:225]
	v_lshl_add_u64 v[134:135], s[30:31], 0, v[134:135]
	v_lshl_add_u64 v[138:139], v[134:135], 0, v[196:197]
	v_pk_mul_f32 v[136:137], v[36:37], v[168:169]
	v_pk_mul_f32 v[134:135], v[34:35], v[166:167]
	global_store_dwordx4 v[138:139], v[134:137], off sc1
	s_nop 1
	v_pk_mul_f32 v[136:137], v[32:33], v[172:173]
	v_pk_mul_f32 v[134:135], v[30:31], v[170:171]
	global_store_dwordx4 v[138:139], v[134:137], off offset:64 sc1
	s_nop 1
	v_pk_mul_f32 v[136:137], v[28:29], v[176:177]
	v_pk_mul_f32 v[134:135], v[26:27], v[174:175]
	global_store_dwordx4 v[138:139], v[134:137], off offset:512 sc1
	s_nop 1
	v_pk_mul_f32 v[136:137], v[24:25], v[180:181]
	v_pk_mul_f32 v[134:135], v[22:23], v[178:179]
	global_store_dwordx4 v[138:139], v[134:137], off offset:576 sc1
	s_nop 1
	v_lshlrev_b64 v[134:135], 12, v[226:227]
	v_lshl_add_u64 v[134:135], s[30:31], 0, v[134:135]
	v_lshl_add_u64 v[138:139], v[134:135], 0, v[196:197]
	v_pk_mul_f32 v[136:137], v[20:21], v[200:201]
	v_pk_mul_f32 v[134:135], v[18:19], v[198:199]
	global_store_dwordx4 v[138:139], v[134:137], off sc1
	s_nop 1
	v_pk_mul_f32 v[136:137], v[16:17], v[204:205]
	v_pk_mul_f32 v[134:135], v[14:15], v[202:203]
	global_store_dwordx4 v[138:139], v[134:137], off offset:64 sc1
	s_nop 1
	v_pk_mul_f32 v[136:137], v[12:13], v[212:213]
	v_pk_mul_f32 v[134:135], v[10:11], v[210:211]
	global_store_dwordx4 v[138:139], v[134:137], off offset:512 sc1
	s_nop 1
	v_pk_mul_f32 v[136:137], v[8:9], v[222:223]
	v_pk_mul_f32 v[134:135], v[6:7], v[220:221]
	global_store_dwordx4 v[138:139], v[134:137], off offset:576 sc1
	s_waitcnt vmcnt(0)
	s_barrier
	v_readfirstlane_b32 s30, v230
	s_lshr_b32 s30, s30, 6
	s_cmp_lg_u32 s30, 0
	s_cbranch_scc1 .Lsp_noinc
	v_readlane_b32 s30, v253, 41
	v_readlane_b32 s31, v253, 29
	s_lshl_b32 s30, s30, 1
	s_cmp_eq_u32 s31, 8
	s_cselect_b32 s31, 1, 0
	s_add_i32 s30, s30, s31
	s_lshl_b32 s30, s30, 2
	s_add_i32 s30, s30, s76
	s_add_i32 s30, s30, 0xffffffc0
	s_lshl_b32 s30, s30, 2
	s_add_i32 s34, s30, 0x8800
	v_readlane_b32 s30, v253, 42
	v_readlane_b32 s31, v253, 43
	s_add_u32 s30, s30, s34
	s_addc_u32 s31, s31, 0
	s_mov_b64 s[36:37], exec
	s_mov_b64 exec, 1
	v_mov_b32_e32 v134, 1
	s_nop 4
	global_atomic_add v1, v134, s[30:31]
	s_mov_b64 exec, s[36:37]
.Lsp_noinc:
	s_cbranch_execnz .LBB0_306
.LBB0_308:
	v_readlane_b32 s30, v253, 41
	v_readlane_b32 s31, v253, 29
	s_lshl_b32 s38, s30, 1
	s_cmp_eq_u32 s31, 8
	s_cselect_b32 s31, 1, 0
	s_add_i32 s38, s38, s31
	s_ashr_i32 s25, s76, 5
	s_mul_i32 s25, s25, 0x18000
	s_add_u32 s36, s18, s25
	s_addc_u32 s37, s19, 0
	v_lshlrev_b64 v[226:227], 2, v[194:195]
	v_ashrrev_i32_e32 v193, 31, v192
	v_lshlrev_b64 v[228:229], 12, v[192:193]
	v_lshl_add_u64 v[244:245], s[36:37], 0, v[226:227]
	global_load_dwordx4 v[198:201], v[244:245], off offset:0
	global_load_dwordx4 v[202:205], v[244:245], off offset:64
	global_load_dwordx4 v[210:213], v[244:245], off offset:512
	global_load_dwordx4 v[214:217], v[244:245], off offset:576
	v_lshl_add_u64 v[242:243], s[12:13], 0, v[226:227]
	v_lshl_add_u64 v[242:243], v[242:243], 0, v[228:229]
	s_mov_b32 s31, 0
	s_mov_b32 s30, 0x0
	v_lshl_add_u64 v[246:247], v[242:243], 0, s[30:31]
	global_load_dwordx4 v[134:137], v[246:247], off offset:0
	global_load_dwordx4 v[138:141], v[246:247], off offset:64
	global_load_dwordx4 v[142:145], v[246:247], off offset:512
	global_load_dwordx4 v[146:149], v[246:247], off offset:576
	s_mov_b32 s30, 0x10000
	v_lshl_add_u64 v[246:247], v[242:243], 0, s[30:31]
	global_load_dwordx4 v[150:153], v[246:247], off offset:0
	global_load_dwordx4 v[154:157], v[246:247], off offset:64
	global_load_dwordx4 v[158:161], v[246:247], off offset:512
	global_load_dwordx4 v[162:165], v[246:247], off offset:576
	s_mov_b32 s30, 0x20000
	v_lshl_add_u64 v[246:247], v[242:243], 0, s[30:31]
	global_load_dwordx4 v[166:169], v[246:247], off offset:0
	global_load_dwordx4 v[170:173], v[246:247], off offset:64
	global_load_dwordx4 v[174:177], v[246:247], off offset:512
	global_load_dwordx4 v[178:181], v[246:247], off offset:576
	s_mov_b32 s30, 0x30000
	v_lshl_add_u64 v[246:247], v[242:243], 0, s[30:31]
	global_load_dwordx4 v[182:185], v[246:247], off offset:0
	global_load_dwordx4 v[186:189], v[246:247], off offset:64
	global_load_dwordx4 v[190:193], v[246:247], off offset:512
	global_load_dwordx4 v[194:197], v[246:247], off offset:576
	s_waitcnt vmcnt(0)
	v_pk_fma_f32 v[130:131], v[130:131], v[198:199], v[134:135]
	v_pk_fma_f32 v[132:133], v[132:133], v[200:201], v[136:137]
	v_pk_fma_f32 v[126:127], v[126:127], v[202:203], v[138:139]
	v_pk_fma_f32 v[128:129], v[128:129], v[204:205], v[140:141]
	v_pk_fma_f32 v[122:123], v[122:123], v[210:211], v[142:143]
	v_pk_fma_f32 v[124:125], v[124:125], v[212:213], v[144:145]
	v_pk_fma_f32 v[118:119], v[118:119], v[214:215], v[146:147]
	v_pk_fma_f32 v[120:121], v[120:121], v[216:217], v[148:149]
	v_pk_fma_f32 v[114:115], v[114:115], v[198:199], v[150:151]
	v_pk_fma_f32 v[116:117], v[116:117], v[200:201], v[152:153]
	v_pk_fma_f32 v[110:111], v[110:111], v[202:203], v[154:155]
	v_pk_fma_f32 v[112:113], v[112:113], v[204:205], v[156:157]
	v_pk_fma_f32 v[106:107], v[106:107], v[210:211], v[158:159]
	v_pk_fma_f32 v[108:109], v[108:109], v[212:213], v[160:161]
	v_pk_fma_f32 v[102:103], v[102:103], v[214:215], v[162:163]
	v_pk_fma_f32 v[104:105], v[104:105], v[216:217], v[164:165]
	v_pk_fma_f32 v[98:99], v[98:99], v[198:199], v[166:167]
	v_pk_fma_f32 v[100:101], v[100:101], v[200:201], v[168:169]
	v_pk_fma_f32 v[94:95], v[94:95], v[202:203], v[170:171]
	v_pk_fma_f32 v[96:97], v[96:97], v[204:205], v[172:173]
	v_pk_fma_f32 v[90:91], v[90:91], v[210:211], v[174:175]
	v_pk_fma_f32 v[92:93], v[92:93], v[212:213], v[176:177]
	v_pk_fma_f32 v[86:87], v[86:87], v[214:215], v[178:179]
	v_pk_fma_f32 v[88:89], v[88:89], v[216:217], v[180:181]
	v_pk_fma_f32 v[82:83], v[82:83], v[198:199], v[182:183]
	v_pk_fma_f32 v[84:85], v[84:85], v[200:201], v[184:185]
	v_pk_fma_f32 v[78:79], v[78:79], v[202:203], v[186:187]
	v_pk_fma_f32 v[80:81], v[80:81], v[204:205], v[188:189]
	v_pk_fma_f32 v[74:75], v[74:75], v[210:211], v[190:191]
	v_pk_fma_f32 v[76:77], v[76:77], v[212:213], v[192:193]
	v_pk_fma_f32 v[70:71], v[70:71], v[214:215], v[194:195]
	v_pk_fma_f32 v[72:73], v[72:73], v[216:217], v[196:197]
	s_mov_b32 s30, 0x80000
	v_lshl_add_u64 v[246:247], v[242:243], 0, s[30:31]
	global_load_dwordx4 v[134:137], v[246:247], off offset:0
	global_load_dwordx4 v[138:141], v[246:247], off offset:64
	global_load_dwordx4 v[142:145], v[246:247], off offset:512
	global_load_dwordx4 v[146:149], v[246:247], off offset:576
	s_mov_b32 s30, 0x90000
	v_lshl_add_u64 v[246:247], v[242:243], 0, s[30:31]
	global_load_dwordx4 v[150:153], v[246:247], off offset:0
	global_load_dwordx4 v[154:157], v[246:247], off offset:64
	global_load_dwordx4 v[158:161], v[246:247], off offset:512
	global_load_dwordx4 v[162:165], v[246:247], off offset:576
	s_mov_b32 s30, 0xa0000
	v_lshl_add_u64 v[246:247], v[242:243], 0, s[30:31]
	global_load_dwordx4 v[166:169], v[246:247], off offset:0
	global_load_dwordx4 v[170:173], v[246:247], off offset:64
	global_load_dwordx4 v[174:177], v[246:247], off offset:512
	global_load_dwordx4 v[178:181], v[246:247], off offset:576
	s_mov_b32 s30, 0xb0000
	v_lshl_add_u64 v[246:247], v[242:243], 0, s[30:31]
	global_load_dwordx4 v[182:185], v[246:247], off offset:0
	global_load_dwordx4 v[186:189], v[246:247], off offset:64
	global_load_dwordx4 v[190:193], v[246:247], off offset:512
	global_load_dwordx4 v[194:197], v[246:247], off offset:576
	s_waitcnt vmcnt(0)
	v_pk_fma_f32 v[66:67], v[66:67], v[198:199], v[134:135]
	v_pk_fma_f32 v[68:69], v[68:69], v[200:201], v[136:137]
	v_pk_fma_f32 v[62:63], v[62:63], v[202:203], v[138:139]
	v_pk_fma_f32 v[64:65], v[64:65], v[204:205], v[140:141]
	v_pk_fma_f32 v[58:59], v[58:59], v[210:211], v[142:143]
	v_pk_fma_f32 v[60:61], v[60:61], v[212:213], v[144:145]
	v_pk_fma_f32 v[54:55], v[54:55], v[214:215], v[146:147]
	v_pk_fma_f32 v[56:57], v[56:57], v[216:217], v[148:149]
	v_pk_fma_f32 v[50:51], v[50:51], v[198:199], v[150:151]
	v_pk_fma_f32 v[52:53], v[52:53], v[200:201], v[152:153]
	v_pk_fma_f32 v[46:47], v[46:47], v[202:203], v[154:155]
	v_pk_fma_f32 v[48:49], v[48:49], v[204:205], v[156:157]
	v_pk_fma_f32 v[42:43], v[42:43], v[210:211], v[158:159]
	v_pk_fma_f32 v[44:45], v[44:45], v[212:213], v[160:161]
	v_pk_fma_f32 v[38:39], v[38:39], v[214:215], v[162:163]
	v_pk_fma_f32 v[40:41], v[40:41], v[216:217], v[164:165]
	v_pk_fma_f32 v[34:35], v[34:35], v[198:199], v[166:167]
	v_pk_fma_f32 v[36:37], v[36:37], v[200:201], v[168:169]
	v_pk_fma_f32 v[30:31], v[30:31], v[202:203], v[170:171]
	v_pk_fma_f32 v[32:33], v[32:33], v[204:205], v[172:173]
	v_pk_fma_f32 v[26:27], v[26:27], v[210:211], v[174:175]
	v_pk_fma_f32 v[28:29], v[28:29], v[212:213], v[176:177]
	v_pk_fma_f32 v[22:23], v[22:23], v[214:215], v[178:179]
	v_pk_fma_f32 v[24:25], v[24:25], v[216:217], v[180:181]
	v_pk_fma_f32 v[18:19], v[18:19], v[198:199], v[182:183]
	v_pk_fma_f32 v[20:21], v[20:21], v[200:201], v[184:185]
	v_pk_fma_f32 v[14:15], v[14:15], v[202:203], v[186:187]
	v_pk_fma_f32 v[16:17], v[16:17], v[204:205], v[188:189]
	v_pk_fma_f32 v[10:11], v[10:11], v[210:211], v[190:191]
	v_pk_fma_f32 v[12:13], v[12:13], v[212:213], v[192:193]
	v_pk_fma_f32 v[6:7], v[6:7], v[214:215], v[194:195]
	v_pk_fma_f32 v[8:9], v[8:9], v[216:217], v[196:197]
	s_cmp_eq_u32 s38, 7
	s_cbranch_scc1 .Lrn_final_p
	s_and_b32 s25, s38, 1
	s_lshr_b32 s30, s38, 1
	s_cmp_eq_u32 s25, 0
	s_cbranch_scc1 .Lrn_ffn_p
	s_add_i32 s30, s30, 1
	s_movk_i32 s25, 0x48
	s_mul_i32 s31, s30, 0x6000
	s_branch .Lrn_p_done

.LBB0_312:
	s_waitcnt vmcnt(0)
	v_readlane_b32 s70, v253, 32
	v_readlane_b32 s71, v253, 33
	v_readlane_b32 s72, v253, 34
	v_readlane_b32 s74, v253, 36
	s_barrier
	s_movk_i32 s67, 0x82
	s_mov_b32 s68, 0xc0135761
	v_readlane_b32 s69, v253, 53
	v_readlane_b32 s73, v253, 35
	v_readlane_b32 s75, v253, 37
	v_readlane_b32 s71, v253, 38
	v_readlane_b32 s25, v253, 41
	v_readfirstlane_b32 s2, v230
	s_lshr_b32 s2, s2, 6
	s_cmp_gt_u32 s2, 3
	s_cbranch_scc1 .Lsn_done
	s_lshl_b32 s3, s84, 2
	s_add_i32 s3, s3, s2
	v_readlane_b32 s4, v253, 29
	s_cmp_eq_u32 s4, 8
	s_cselect_b32 s6, 1, 0
	s_cselect_b32 s7, 44, 32
	s_lshl_b32 s5, s25, 1
	s_add_i32 s5, s5, s6
	v_readlane_b32 s8, v253, 42
	v_readlane_b32 s9, v253, 43
	s_lshr_b32 s10, s3, 8
	s_lshl_b32 s11, s5, 2
	s_add_i32 s11, s11, s10
	s_lshl_b32 s11, s11, 2
	s_add_i32 s11, s11, 0x8800
	s_add_u32 s12, s8, s11
	s_addc_u32 s13, s9, 0
	s_mov_b32 s14, 0
.Lsn_poll:
	global_load_dword v134, v1, s[12:13] sc1
	s_waitcnt vmcnt(0)
	v_readfirstlane_b32 s15, v134
	s_cmp_ge_u32 s15, s7
	s_cbranch_scc1 .Lsn_ready
	s_sleep 1
	s_add_i32 s14, s14, 1
	s_cmp_lt_u32 s14, 0x10000
	s_cbranch_scc1 .Lsn_poll
.Lsn_ready:
	v_mbcnt_lo_u32_b32 v142, -1, 0
	v_mbcnt_hi_u32_b32 v142, -1, v142
	v_lshlrev_b32_e32 v143, 3, v142
	v_lshlrev_b32_e32 v142, 4, v142
	s_load_dwordx2 s[16:17], s[54:55], 0xd8
	s_add_i32 s18, s3, 0x4000
	s_lshl_b32 s19, s18, 12
	s_waitcnt lgkmcnt(0)
	s_add_u32 s16, s16, s19
	s_addc_u32 s17, s17, 0
	global_load_dwordx4 v[6:9], v142, s[16:17] offset:0
	global_load_dwordx4 v[10:13], v142, s[16:17] offset:1024
	global_load_dwordx4 v[14:17], v142, s[16:17] offset:2048
	global_load_dwordx4 v[18:21], v142, s[16:17] offset:3072
	s_lshl_b32 s19, s3, 12
	s_add_u32 s20, s8, s19
	s_addc_u32 s21, s9, 0
	s_add_u32 s20, s20, 0x15e00000
	s_addc_u32 s21, s21, 0
	s_add_u32 s22, s20, 0x0
	s_addc_u32 s23, s21, 0
	global_load_dwordx4 v[22:25], v142, s[22:23] offset:0 sc1
	global_load_dwordx4 v[26:29], v142, s[22:23] offset:1024 sc1
	global_load_dwordx4 v[30:33], v142, s[22:23] offset:2048 sc1
	global_load_dwordx4 v[34:37], v142, s[22:23] offset:3072 sc1
	s_add_u32 s22, s20, 0x400000
	s_addc_u32 s23, s21, 0
	global_load_dwordx4 v[38:41], v142, s[22:23] offset:0 sc1
	global_load_dwordx4 v[42:45], v142, s[22:23] offset:1024 sc1
	global_load_dwordx4 v[46:49], v142, s[22:23] offset:2048 sc1
	global_load_dwordx4 v[50:53], v142, s[22:23] offset:3072 sc1
	s_add_u32 s22, s20, 0x800000
	s_addc_u32 s23, s21, 0
	global_load_dwordx4 v[54:57], v142, s[22:23] offset:0 sc1
	global_load_dwordx4 v[58:61], v142, s[22:23] offset:1024 sc1
	global_load_dwordx4 v[62:65], v142, s[22:23] offset:2048 sc1
	global_load_dwordx4 v[66:69], v142, s[22:23] offset:3072 sc1
	s_add_u32 s22, s20, 0xc00000
	s_addc_u32 s23, s21, 0
	global_load_dwordx4 v[70:73], v142, s[22:23] offset:0 sc1
	global_load_dwordx4 v[74:77], v142, s[22:23] offset:1024 sc1
	global_load_dwordx4 v[78:81], v142, s[22:23] offset:2048 sc1
	global_load_dwordx4 v[82:85], v142, s[22:23] offset:3072 sc1
	s_waitcnt vmcnt(0)
	v_pk_add_f32 v[6:7], v[6:7], v[22:23]
	v_pk_add_f32 v[8:9], v[8:9], v[24:25]
	v_pk_add_f32 v[10:11], v[10:11], v[26:27]
	v_pk_add_f32 v[12:13], v[12:13], v[28:29]
	v_pk_add_f32 v[14:15], v[14:15], v[30:31]
	v_pk_add_f32 v[16:17], v[16:17], v[32:33]
	v_pk_add_f32 v[18:19], v[18:19], v[34:35]
	v_pk_add_f32 v[20:21], v[20:21], v[36:37]
	v_pk_add_f32 v[6:7], v[6:7], v[38:39]
	v_pk_add_f32 v[8:9], v[8:9], v[40:41]
	v_pk_add_f32 v[10:11], v[10:11], v[42:43]
	v_pk_add_f32 v[12:13], v[12:13], v[44:45]
	v_pk_add_f32 v[14:15], v[14:15], v[46:47]
	v_pk_add_f32 v[16:17], v[16:17], v[48:49]
	v_pk_add_f32 v[18:19], v[18:19], v[50:51]
	v_pk_add_f32 v[20:21], v[20:21], v[52:53]
	v_pk_add_f32 v[6:7], v[6:7], v[54:55]
	v_pk_add_f32 v[8:9], v[8:9], v[56:57]
	v_pk_add_f32 v[10:11], v[10:11], v[58:59]
	v_pk_add_f32 v[12:13], v[12:13], v[60:61]
	v_pk_add_f32 v[14:15], v[14:15], v[62:63]
	v_pk_add_f32 v[16:17], v[16:17], v[64:65]
	v_pk_add_f32 v[18:19], v[18:19], v[66:67]
	v_pk_add_f32 v[20:21], v[20:21], v[68:69]
	v_pk_add_f32 v[6:7], v[6:7], v[70:71]
	v_pk_add_f32 v[8:9], v[8:9], v[72:73]
	v_pk_add_f32 v[10:11], v[10:11], v[74:75]
	v_pk_add_f32 v[12:13], v[12:13], v[76:77]
	v_pk_add_f32 v[14:15], v[14:15], v[78:79]
	v_pk_add_f32 v[16:17], v[16:17], v[80:81]
	v_pk_add_f32 v[18:19], v[18:19], v[82:83]
	v_pk_add_f32 v[20:21], v[20:21], v[84:85]
	s_add_u32 s22, s20, 0x1000000
	s_addc_u32 s23, s21, 0
	global_load_dwordx4 v[22:25], v142, s[22:23] offset:0 sc1
	global_load_dwordx4 v[26:29], v142, s[22:23] offset:1024 sc1
	global_load_dwordx4 v[30:33], v142, s[22:23] offset:2048 sc1
	global_load_dwordx4 v[34:37], v142, s[22:23] offset:3072 sc1
	s_add_u32 s22, s20, 0x1400000
	s_addc_u32 s23, s21, 0
	global_load_dwordx4 v[38:41], v142, s[22:23] offset:0 sc1
	global_load_dwordx4 v[42:45], v142, s[22:23] offset:1024 sc1
	global_load_dwordx4 v[46:49], v142, s[22:23] offset:2048 sc1
	global_load_dwordx4 v[50:53], v142, s[22:23] offset:3072 sc1
	s_add_u32 s22, s20, 0x1800000
	s_addc_u32 s23, s21, 0
	global_load_dwordx4 v[54:57], v142, s[22:23] offset:0 sc1
	global_load_dwordx4 v[58:61], v142, s[22:23] offset:1024 sc1
	global_load_dwordx4 v[62:65], v142, s[22:23] offset:2048 sc1
	global_load_dwordx4 v[66:69], v142, s[22:23] offset:3072 sc1
	s_add_u32 s22, s20, 0x1c00000
	s_addc_u32 s23, s21, 0
	global_load_dwordx4 v[70:73], v142, s[22:23] offset:0 sc1
	global_load_dwordx4 v[74:77], v142, s[22:23] offset:1024 sc1
	global_load_dwordx4 v[78:81], v142, s[22:23] offset:2048 sc1
	global_load_dwordx4 v[82:85], v142, s[22:23] offset:3072 sc1
	s_waitcnt vmcnt(0)
	v_pk_add_f32 v[6:7], v[6:7], v[22:23]
	v_pk_add_f32 v[8:9], v[8:9], v[24:25]
	v_pk_add_f32 v[10:11], v[10:11], v[26:27]
	v_pk_add_f32 v[12:13], v[12:13], v[28:29]
	v_pk_add_f32 v[14:15], v[14:15], v[30:31]
	v_pk_add_f32 v[16:17], v[16:17], v[32:33]
	v_pk_add_f32 v[18:19], v[18:19], v[34:35]
	v_pk_add_f32 v[20:21], v[20:21], v[36:37]
	v_pk_add_f32 v[6:7], v[6:7], v[38:39]
	v_pk_add_f32 v[8:9], v[8:9], v[40:41]
	v_pk_add_f32 v[10:11], v[10:11], v[42:43]
	v_pk_add_f32 v[12:13], v[12:13], v[44:45]
	v_pk_add_f32 v[14:15], v[14:15], v[46:47]
	v_pk_add_f32 v[16:17], v[16:17], v[48:49]
	v_pk_add_f32 v[18:19], v[18:19], v[50:51]
	v_pk_add_f32 v[20:21], v[20:21], v[52:53]
	v_pk_add_f32 v[6:7], v[6:7], v[54:55]
	v_pk_add_f32 v[8:9], v[8:9], v[56:57]
	v_pk_add_f32 v[10:11], v[10:11], v[58:59]
	v_pk_add_f32 v[12:13], v[12:13], v[60:61]
	v_pk_add_f32 v[14:15], v[14:15], v[62:63]
	v_pk_add_f32 v[16:17], v[16:17], v[64:65]
	v_pk_add_f32 v[18:19], v[18:19], v[66:67]
	v_pk_add_f32 v[20:21], v[20:21], v[68:69]
	v_pk_add_f32 v[6:7], v[6:7], v[70:71]
	v_pk_add_f32 v[8:9], v[8:9], v[72:73]
	v_pk_add_f32 v[10:11], v[10:11], v[74:75]
	v_pk_add_f32 v[12:13], v[12:13], v[76:77]
	v_pk_add_f32 v[14:15], v[14:15], v[78:79]
	v_pk_add_f32 v[16:17], v[16:17], v[80:81]
	v_pk_add_f32 v[18:19], v[18:19], v[82:83]
	v_pk_add_f32 v[20:21], v[20:21], v[84:85]
	s_cmp_lg_u32 s7, 44
	s_cbranch_scc1 .Lsn_sum
	s_add_u32 s22, s20, 0x2000000
	s_addc_u32 s23, s21, 0
	global_load_dwordx4 v[22:25], v142, s[22:23] offset:0 sc1
	global_load_dwordx4 v[26:29], v142, s[22:23] offset:1024 sc1
	global_load_dwordx4 v[30:33], v142, s[22:23] offset:2048 sc1
	global_load_dwordx4 v[34:37], v142, s[22:23] offset:3072 sc1
	s_add_u32 s22, s20, 0x2400000
	s_addc_u32 s23, s21, 0
	global_load_dwordx4 v[38:41], v142, s[22:23] offset:0 sc1
	global_load_dwordx4 v[42:45], v142, s[22:23] offset:1024 sc1
	global_load_dwordx4 v[46:49], v142, s[22:23] offset:2048 sc1
	global_load_dwordx4 v[50:53], v142, s[22:23] offset:3072 sc1
	s_add_u32 s22, s20, 0x2800000
	s_addc_u32 s23, s21, 0
	global_load_dwordx4 v[54:57], v142, s[22:23] offset:0 sc1
	global_load_dwordx4 v[58:61], v142, s[22:23] offset:1024 sc1
	global_load_dwordx4 v[62:65], v142, s[22:23] offset:2048 sc1
	global_load_dwordx4 v[66:69], v142, s[22:23] offset:3072 sc1
	s_waitcnt vmcnt(0)
	v_pk_add_f32 v[6:7], v[6:7], v[22:23]
	v_pk_add_f32 v[8:9], v[8:9], v[24:25]
	v_pk_add_f32 v[10:11], v[10:11], v[26:27]
	v_pk_add_f32 v[12:13], v[12:13], v[28:29]
	v_pk_add_f32 v[14:15], v[14:15], v[30:31]
	v_pk_add_f32 v[16:17], v[16:17], v[32:33]
	v_pk_add_f32 v[18:19], v[18:19], v[34:35]
	v_pk_add_f32 v[20:21], v[20:21], v[36:37]
	v_pk_add_f32 v[6:7], v[6:7], v[38:39]
	v_pk_add_f32 v[8:9], v[8:9], v[40:41]
	v_pk_add_f32 v[10:11], v[10:11], v[42:43]
	v_pk_add_f32 v[12:13], v[12:13], v[44:45]
	v_pk_add_f32 v[14:15], v[14:15], v[46:47]
	v_pk_add_f32 v[16:17], v[16:17], v[48:49]
	v_pk_add_f32 v[18:19], v[18:19], v[50:51]
	v_pk_add_f32 v[20:21], v[20:21], v[52:53]
	v_pk_add_f32 v[6:7], v[6:7], v[54:55]
	v_pk_add_f32 v[8:9], v[8:9], v[56:57]
	v_pk_add_f32 v[10:11], v[10:11], v[58:59]
	v_pk_add_f32 v[12:13], v[12:13], v[60:61]
	v_pk_add_f32 v[14:15], v[14:15], v[62:63]
	v_pk_add_f32 v[16:17], v[16:17], v[64:65]
	v_pk_add_f32 v[18:19], v[18:19], v[66:67]
	v_pk_add_f32 v[20:21], v[20:21], v[68:69]
.Lsn_sum:
	s_cmp_eq_u32 s5, 7
	s_cbranch_scc1 .Lsn_final_p
	s_cmp_eq_u32 s6, 0
	s_cbranch_scc1 .Lsn_ffn_p
	s_add_i32 s24, s25, 1
	s_movk_i32 s26, 0x48
	s_mul_i32 s27, s24, 0x6000
	s_branch .Lsn_p_done
.Lsn_ffn_p:
	s_mov_b32 s24, s25
	s_movk_i32 s26, 0x50
	s_mul_i32 s27, s24, 0x6000
	s_add_i32 s27, s27, 0x3000
	s_branch .Lsn_p_done
.Lsn_final_p:
	s_mov_b32 s24, 0
	s_movk_i32 s26, 0xd0
	s_mov_b32 s27, 0
.Lsn_p_done:
	s_load_dwordx2 s[28:29], s[54:55], s26
	s_lshl_b32 s24, s24, 12
	s_waitcnt lgkmcnt(0)
	s_add_u32 s28, s28, s24
	s_addc_u32 s29, s29, 0
	global_load_dwordx4 v[86:89], v142, s[28:29] offset:0
	global_load_dwordx4 v[90:93], v142, s[28:29] offset:1024
	global_load_dwordx4 v[94:97], v142, s[28:29] offset:2048
	global_load_dwordx4 v[98:101], v142, s[28:29] offset:3072
	v_mov_b32_e32 v102, 0
	v_mov_b32_e32 v118, 0
	v_mov_b32_e32 v103, 0
	v_mov_b32_e32 v119, 0
	v_mov_b32_e32 v104, 0
	v_mov_b32_e32 v120, 0
	v_mov_b32_e32 v105, 0
	v_mov_b32_e32 v121, 0
	v_mov_b32_e32 v106, 0
	v_mov_b32_e32 v122, 0
	v_mov_b32_e32 v107, 0
	v_mov_b32_e32 v123, 0
	v_mov_b32_e32 v108, 0
	v_mov_b32_e32 v124, 0
	v_mov_b32_e32 v109, 0
	v_mov_b32_e32 v125, 0
	v_mov_b32_e32 v110, 0
	v_mov_b32_e32 v126, 0
	v_mov_b32_e32 v111, 0
	v_mov_b32_e32 v127, 0
	v_mov_b32_e32 v112, 0
	v_mov_b32_e32 v128, 0
	v_mov_b32_e32 v113, 0
	v_mov_b32_e32 v129, 0
	v_mov_b32_e32 v114, 0
	v_mov_b32_e32 v130, 0
	v_mov_b32_e32 v115, 0
	v_mov_b32_e32 v131, 0
	v_mov_b32_e32 v116, 0
	v_mov_b32_e32 v132, 0
	v_mov_b32_e32 v117, 0
	v_mov_b32_e32 v133, 0
	s_cmp_eq_u32 s5, 7
	s_cbranch_scc1 .Lsn_nomod
	v_readlane_b32 s28, v253, 34
	v_readlane_b32 s29, v253, 35
	s_lshr_b32 s30, s3, 3
	s_add_i32 s30, s30, 2
	s_mul_i32 s30, s30, 0x18000
	s_add_i32 s30, s30, s27
	s_add_u32 s28, s28, s30
	s_addc_u32 s29, s29, 0
	global_load_dwordx4 v[102:105], v142, s[28:29] offset:0
	global_load_dwordx4 v[106:109], v142, s[28:29] offset:1024
	global_load_dwordx4 v[110:113], v142, s[28:29] offset:2048
	global_load_dwordx4 v[114:117], v142, s[28:29] offset:3072
	s_add_u32 s28, s28, 0x1000
	s_addc_u32 s29, s29, 0
	global_load_dwordx4 v[118:121], v142, s[28:29] offset:0
	global_load_dwordx4 v[122:125], v142, s[28:29] offset:1024
	global_load_dwordx4 v[126:129], v142, s[28:29] offset:2048
	global_load_dwordx4 v[130:133], v142, s[28:29] offset:3072
.Lsn_nomod:
	v_pk_mul_f32 v[134:135], v[6:7], v[6:7]
	v_pk_fma_f32 v[134:135], v[8:9], v[8:9], v[134:135]
	v_pk_fma_f32 v[134:135], v[10:11], v[10:11], v[134:135]
	v_pk_fma_f32 v[134:135], v[12:13], v[12:13], v[134:135]
	v_pk_fma_f32 v[134:135], v[14:15], v[14:15], v[134:135]
	v_pk_fma_f32 v[134:135], v[16:17], v[16:17], v[134:135]
	v_pk_fma_f32 v[134:135], v[18:19], v[18:19], v[134:135]
	v_pk_fma_f32 v[134:135], v[20:21], v[20:21], v[134:135]
	v_add_f32_e32 v134, v134, v135
	s_nop 1
	v_add_f32_dpp v134, v134, v134 quad_perm:[1,0,3,2] row_mask:0xf bank_mask:0xf
	s_nop 1
	v_add_f32_dpp v134, v134, v134 quad_perm:[2,3,0,1] row_mask:0xf bank_mask:0xf
	s_nop 1
	v_add_f32_dpp v134, v134, v134 row_half_mirror row_mask:0xf bank_mask:0xf
	s_nop 1
	v_add_f32_dpp v134, v134, v134 row_mirror row_mask:0xf bank_mask:0xf
	s_nop 1
	v_add_f32_dpp v134, v134, v134 row_bcast:15 row_mask:0xa bank_mask:0xf
	s_nop 1
	v_add_f32_dpp v134, v134, v134 row_bcast:31 row_mask:0xc bank_mask:0xf
	s_nop 1
	v_readlane_b32 s30, v134, 63
	s_nop 1
	v_mov_b32_e32 v136, s30
	v_fmamk_f32 v136, v136, 0x3a800000, v232
	v_rsq_f32_e32 v136, v136
	s_nop 0
	v_mov_b32_e32 v137, v136
	s_waitcnt vmcnt(0)
	s_lshl_b32 s19, s18, 11
	s_add_u32 s30, s8, s19
	s_addc_u32 s31, s9, 0
	s_add_u32 s30, s30, 0x7400000
	s_addc_u32 s31, s31, 0
	s_cmp_eq_u32 s5, 7
	s_cbranch_scc1 .Lsn_final_out
	global_store_dwordx4 v142, v[6:9], s[16:17] offset:0
	global_store_dwordx4 v142, v[10:13], s[16:17] offset:1024
	global_store_dwordx4 v142, v[14:17], s[16:17] offset:2048
	global_store_dwordx4 v142, v[18:21], s[16:17] offset:3072
	v_pk_add_f32 v[118:119], v[118:119], 1.0 op_sel_hi:[1,0]
	v_pk_mul_f32 v[86:87], v[86:87], v[118:119]
	v_pk_mul_f32 v[138:139], v[6:7], v[136:137]
	v_pk_fma_f32 v[138:139], v[138:139], v[86:87], v[102:103]
	v_pk_add_f32 v[120:121], v[120:121], 1.0 op_sel_hi:[1,0]
	v_pk_mul_f32 v[88:89], v[88:89], v[120:121]
	v_pk_mul_f32 v[140:141], v[8:9], v[136:137]
	v_pk_fma_f32 v[140:141], v[140:141], v[88:89], v[104:105]
	v_cvt_pk_bf16_f32 v144, v138, v139
	v_cvt_pk_bf16_f32 v145, v140, v141
	global_store_dwordx2 v143, v[144:145], s[30:31] offset:0
	v_pk_add_f32 v[122:123], v[122:123], 1.0 op_sel_hi:[1,0]
	v_pk_mul_f32 v[90:91], v[90:91], v[122:123]
	v_pk_mul_f32 v[138:139], v[10:11], v[136:137]
	v_pk_fma_f32 v[138:139], v[138:139], v[90:91], v[106:107]
	v_pk_add_f32 v[124:125], v[124:125], 1.0 op_sel_hi:[1,0]
	v_pk_mul_f32 v[92:93], v[92:93], v[124:125]
	v_pk_mul_f32 v[140:141], v[12:13], v[136:137]
	v_pk_fma_f32 v[140:141], v[140:141], v[92:93], v[108:109]
	v_cvt_pk_bf16_f32 v146, v138, v139
	v_cvt_pk_bf16_f32 v147, v140, v141
	global_store_dwordx2 v143, v[146:147], s[30:31] offset:512
	v_pk_add_f32 v[126:127], v[126:127], 1.0 op_sel_hi:[1,0]
	v_pk_mul_f32 v[94:95], v[94:95], v[126:127]
	v_pk_mul_f32 v[138:139], v[14:15], v[136:137]
	v_pk_fma_f32 v[138:139], v[138:139], v[94:95], v[110:111]
	v_pk_add_f32 v[128:129], v[128:129], 1.0 op_sel_hi:[1,0]
	v_pk_mul_f32 v[96:97], v[96:97], v[128:129]
	v_pk_mul_f32 v[140:141], v[16:17], v[136:137]
	v_pk_fma_f32 v[140:141], v[140:141], v[96:97], v[112:113]
	v_cvt_pk_bf16_f32 v148, v138, v139
	v_cvt_pk_bf16_f32 v149, v140, v141
	global_store_dwordx2 v143, v[148:149], s[30:31] offset:1024
	v_pk_add_f32 v[130:131], v[130:131], 1.0 op_sel_hi:[1,0]
	v_pk_mul_f32 v[98:99], v[98:99], v[130:131]
	v_pk_mul_f32 v[138:139], v[18:19], v[136:137]
	v_pk_fma_f32 v[138:139], v[138:139], v[98:99], v[114:115]
	v_pk_add_f32 v[132:133], v[132:133], 1.0 op_sel_hi:[1,0]
	v_pk_mul_f32 v[100:101], v[100:101], v[132:133]
	v_pk_mul_f32 v[140:141], v[20:21], v[136:137]
	v_pk_fma_f32 v[140:141], v[140:141], v[100:101], v[116:117]
	v_cvt_pk_bf16_f32 v150, v138, v139
	v_cvt_pk_bf16_f32 v151, v140, v141
	global_store_dwordx2 v143, v[150:151], s[30:31] offset:1536
	s_branch .Lsn_done
.Lsn_final_out:
	v_pk_mul_f32 v[6:7], v[6:7], v[136:137]
	v_pk_mul_f32 v[6:7], v[6:7], v[86:87]
	v_pk_mul_f32 v[8:9], v[8:9], v[136:137]
	v_pk_mul_f32 v[8:9], v[8:9], v[88:89]
	global_store_dwordx4 v142, v[6:9], s[16:17] offset:0
	v_pk_mul_f32 v[10:11], v[10:11], v[136:137]
	v_pk_mul_f32 v[10:11], v[10:11], v[90:91]
	v_pk_mul_f32 v[12:13], v[12:13], v[136:137]
	v_pk_mul_f32 v[12:13], v[12:13], v[92:93]
	global_store_dwordx4 v142, v[10:13], s[16:17] offset:1024
	v_pk_mul_f32 v[14:15], v[14:15], v[136:137]
	v_pk_mul_f32 v[14:15], v[14:15], v[94:95]
	v_pk_mul_f32 v[16:17], v[16:17], v[136:137]
	v_pk_mul_f32 v[16:17], v[16:17], v[96:97]
	global_store_dwordx4 v142, v[14:17], s[16:17] offset:2048
	v_pk_mul_f32 v[18:19], v[18:19], v[136:137]
	v_pk_mul_f32 v[18:19], v[18:19], v[98:99]
	v_pk_mul_f32 v[20:21], v[20:21], v[136:137]
	v_pk_mul_f32 v[20:21], v[20:21], v[100:101]
	global_store_dwordx4 v142, v[18:21], s[16:17] offset:3072
.Lsn_done:
.LBB0_313:
	s_mov_b64 s[2:3], 0
